# stack5 + attention QK K-fragment LDS reads issued up front (separate registers) in 9 tile blocks
# speedup vs baseline: 1.0153x; 1.0074x over previous
.LBB0_2559:
	s_waitcnt vmcnt(7)
	v_mov_b32_e32 v4, v0
	s_lshl_b32 s0, s4, 10
	v_and_b32_e32 v144, 3, v4
	v_lshl_or_b32 v134, v144, 8, s0
	v_lshl_add_u64 v[2:3], s[38:39], 0, v[134:135]
	v_and_b32_e32 v134, 48, v4
	v_bfe_u32 v145, v4, 4, 2
	s_waitcnt vmcnt(5)
	v_lshl_add_u64 v[14:15], v[2:3], 0, v[134:135]
	v_and_b32_e32 v146, 63, v4
	v_and_b32_e32 v1, 15, v4
	global_load_dwordx4 v[2:5], v[14:15], off
	global_load_dwordx4 v[6:9], v[14:15], off offset:64
	global_load_dwordx4 v[10:13], v[14:15], off offset:128
	v_lshl_add_u32 v142, v145, 2, v138
	global_load_dwordx4 v[14:17], v[14:15], off offset:192
	s_waitcnt vmcnt(11)
	ds_read2_b32 v[18:19], v142 offset1:4
	ds_read2_b32 v[20:21], v142 offset0:8 offset1:12
	s_lshl_b32 s0, s4, 8
	s_waitcnt vmcnt(7)
	ds_read2_b32 v[26:27], v142 offset0:40 offset1:44
	s_add_u32 s0, s58, s0
	s_waitcnt lgkmcnt(2)
	v_add_u32_e32 v22, s48, v18
	v_add_u32_e32 v18, s48, v19
	s_addc_u32 s1, s59, 0
	v_lshlrev_b32_e32 v114, 4, v1
	v_mov_b32_e32 v115, v135
	v_ashrrev_i32_e32 v23, 31, v22
	v_ashrrev_i32_e32 v19, 31, v18
	v_lshl_add_u64 v[136:137], s[0:1], 0, v[114:115]
	v_lshlrev_b64 v[22:23], 9, v[22:23]
	v_lshlrev_b64 v[18:19], 9, v[18:19]
	v_lshl_add_u64 v[22:23], v[136:137], 0, v[22:23]
	v_lshl_add_u64 v[18:19], v[136:137], 0, v[18:19]
	global_load_dwordx4 v[42:45], v[22:23], off
	global_load_dwordx4 v[50:53], v[18:19], off
	s_waitcnt lgkmcnt(1)
	v_add_u32_e32 v18, s48, v20
	s_waitcnt lgkmcnt(0)
	v_add_u32_e32 v28, s48, v26
	v_add_u32_e32 v26, s48, v27
	s_waitcnt vmcnt(7)
	ds_read2_b32 v[58:59], v142 offset0:72 offset1:76
	v_ashrrev_i32_e32 v19, 31, v18
	v_ashrrev_i32_e32 v27, 31, v26
	v_lshlrev_b64 v[18:19], 9, v[18:19]
	v_lshlrev_b64 v[26:27], 9, v[26:27]
	v_lshl_add_u64 v[18:19], v[136:137], 0, v[18:19]
	v_lshl_add_u64 v[26:27], v[136:137], 0, v[26:27]
	global_load_dwordx4 v[54:57], v[18:19], off
	global_load_dwordx4 v[38:41], v[26:27], off
	ds_read2_b32 v[26:27], v142 offset0:48 offset1:52
	s_waitcnt vmcnt(8) lgkmcnt(1)
	v_add_u32_e32 v46, s48, v58
	v_ashrrev_i32_e32 v29, 31, v28
	v_ashrrev_i32_e32 v47, 31, v46
	v_lshlrev_b64 v[28:29], 9, v[28:29]
	v_lshlrev_b64 v[46:47], 9, v[46:47]
	v_lshl_add_u64 v[28:29], v[136:137], 0, v[28:29]
	v_lshl_add_u64 v[46:47], v[136:137], 0, v[46:47]
	v_add_u32_e32 v18, s48, v21
	global_load_dwordx4 v[34:37], v[28:29], off
	v_ashrrev_i32_e32 v19, 31, v18
	global_load_dwordx4 v[46:49], v[46:47], off
	s_waitcnt lgkmcnt(0)
	v_add_u32_e32 v28, s48, v26
	v_add_u32_e32 v26, s48, v27
	v_ashrrev_i32_e32 v27, 31, v26
	v_lshlrev_b64 v[18:19], 9, v[18:19]
	v_lshlrev_b64 v[26:27], 9, v[26:27]
	v_lshl_add_u64 v[18:19], v[136:137], 0, v[18:19]
	v_lshl_add_u64 v[26:27], v[136:137], 0, v[26:27]
	global_load_dwordx4 v[66:69], v[18:19], off
	global_load_dwordx4 v[70:73], v[26:27], off
	ds_read2_b32 v[18:19], v142 offset0:16 offset1:20
	ds_read2_b32 v[26:27], v142 offset0:56 offset1:60
	v_add_u32_e32 v58, s48, v59
	v_ashrrev_i32_e32 v29, 31, v28
	v_ashrrev_i32_e32 v59, 31, v58
	s_waitcnt lgkmcnt(1)
	v_add_u32_e32 v20, s48, v18
	v_add_u32_e32 v18, s48, v19
	v_ashrrev_i32_e32 v21, 31, v20
	v_ashrrev_i32_e32 v19, 31, v18
	v_lshlrev_b64 v[20:21], 9, v[20:21]
	v_lshlrev_b64 v[18:19], 9, v[18:19]
	v_lshl_add_u64 v[20:21], v[136:137], 0, v[20:21]
	v_lshl_add_u64 v[18:19], v[136:137], 0, v[18:19]
	global_load_dwordx4 v[78:81], v[20:21], off
	global_load_dwordx4 v[90:93], v[18:19], off
	ds_read2_b32 v[18:19], v142 offset0:24 offset1:28
	v_lshlrev_b64 v[28:29], 9, v[28:29]
	v_lshlrev_b64 v[58:59], 9, v[58:59]
	ds_read2_b32 v[22:23], v142 offset0:32 offset1:36
	v_lshl_add_u64 v[28:29], v[136:137], 0, v[28:29]
	s_waitcnt lgkmcnt(1)
	v_add_u32_e32 v20, s48, v18
	v_ashrrev_i32_e32 v21, 31, v20
	v_add_u32_e32 v18, s48, v19
	v_lshlrev_b64 v[20:21], 9, v[20:21]
	v_ashrrev_i32_e32 v19, 31, v18
	v_lshl_add_u64 v[20:21], v[136:137], 0, v[20:21]
	v_lshlrev_b64 v[18:19], 9, v[18:19]
	global_load_dwordx4 v[102:105], v[20:21], off
	v_lshl_add_u64 v[18:19], v[136:137], 0, v[18:19]
	global_load_dwordx4 v[110:113], v[18:19], off
	ds_read2_b32 v[30:31], v142 offset0:64 offset1:68
	v_lshl_add_u64 v[58:59], v[136:137], 0, v[58:59]
	ds_read2_b32 v[82:83], v142 offset0:80 offset1:84
	ds_read2_b32 v[106:107], v142 offset0:88 offset1:92
	global_load_dwordx4 v[62:65], v[28:29], off
	s_waitcnt lgkmcnt(3)
	v_add_u32_e32 v18, s48, v22
	global_load_dwordx4 v[58:61], v[58:59], off
	v_add_u32_e32 v28, s48, v26
	v_add_u32_e32 v26, s48, v27
	v_ashrrev_i32_e32 v29, 31, v28
	v_ashrrev_i32_e32 v27, 31, v26
	v_lshlrev_b64 v[28:29], 9, v[28:29]
	v_lshlrev_b64 v[26:27], 9, v[26:27]
	v_lshl_add_u64 v[28:29], v[136:137], 0, v[28:29]
	v_lshl_add_u64 v[26:27], v[136:137], 0, v[26:27]
	v_add_u32_e32 v22, s48, v23
	global_load_dwordx4 v[86:89], v[28:29], off
	global_load_dwordx4 v[94:97], v[26:27], off
	s_waitcnt lgkmcnt(2)
	v_add_u32_e32 v26, s48, v30
	v_add_u32_e32 v30, s48, v31
	s_waitcnt lgkmcnt(1)
	v_add_u32_e32 v74, s48, v82
	v_add_u32_e32 v82, s48, v83
	s_waitcnt lgkmcnt(0)
	v_add_u32_e32 v98, s48, v106
	v_add_u32_e32 v106, s48, v107
	v_ashrrev_i32_e32 v19, 31, v18
	v_ashrrev_i32_e32 v23, 31, v22
	v_ashrrev_i32_e32 v27, 31, v26
	v_ashrrev_i32_e32 v31, 31, v30
	v_ashrrev_i32_e32 v75, 31, v74
	v_ashrrev_i32_e32 v83, 31, v82
	v_ashrrev_i32_e32 v99, 31, v98
	v_ashrrev_i32_e32 v107, 31, v106
	v_lshlrev_b64 v[18:19], 9, v[18:19]
	v_lshlrev_b64 v[22:23], 9, v[22:23]
	v_lshlrev_b64 v[26:27], 9, v[26:27]
	v_lshlrev_b64 v[30:31], 9, v[30:31]
	v_lshlrev_b64 v[74:75], 9, v[74:75]
	v_lshlrev_b64 v[82:83], 9, v[82:83]
	v_lshlrev_b64 v[98:99], 9, v[98:99]
	v_lshlrev_b64 v[106:107], 9, v[106:107]
	v_add_u32_e32 v139, v138, v114
	v_lshl_add_u64 v[18:19], v[136:137], 0, v[18:19]
	v_lshl_add_u64 v[22:23], v[136:137], 0, v[22:23]
	v_lshl_add_u64 v[26:27], v[136:137], 0, v[26:27]
	v_lshl_add_u64 v[30:31], v[136:137], 0, v[30:31]
	v_lshl_add_u64 v[74:75], v[136:137], 0, v[74:75]
	v_lshl_add_u64 v[82:83], v[136:137], 0, v[82:83]
	v_lshl_add_u64 v[98:99], v[136:137], 0, v[98:99]
	v_lshl_add_u64 v[106:107], v[136:137], 0, v[106:107]
	v_mad_u32_u24 v143, v145, s33, v139
	global_load_dwordx4 v[18:21], v[18:19], off
	v_add_u32_e32 v118, v138, v134
	global_load_dwordx4 v[22:25], v[22:23], off
	v_cmp_lt_u32_e64 s[10:11], 3, v1
	global_load_dwordx4 v[26:29], v[26:27], off
	v_mad_u32_u24 v119, v1, s33, v118
	global_load_dwordx4 v[30:33], v[30:31], off
	s_waitcnt vmcnt(23)
	v_cndmask_b32_e64 v5, v5, 0, s[10:11]
	global_load_dwordx4 v[74:77], v[74:75], off
	v_cndmask_b32_e64 v4, v4, 0, s[10:11]
	global_load_dwordx4 v[82:85], v[82:83], off
	v_cndmask_b32_e64 v3, v3, 0, s[10:11]
	global_load_dwordx4 v[98:101], v[98:99], off
	v_cndmask_b32_e64 v2, v2, 0, s[10:11]
	global_load_dwordx4 v[106:109], v[106:107], off
	s_waitcnt vmcnt(23)
	ds_write_b128 v143, v[42:45] offset:7168
	s_waitcnt vmcnt(22)
	ds_write_b128 v143, v[50:53] offset:8448
	s_waitcnt vmcnt(21)
	ds_write_b128 v143, v[54:57] offset:9728
	s_waitcnt vmcnt(17)
	ds_write_b128 v143, v[66:69] offset:11008
	s_waitcnt vmcnt(15)
	ds_write_b128 v143, v[78:81] offset:12288
	s_waitcnt vmcnt(14)
	ds_write_b128 v143, v[90:93] offset:13568
	s_waitcnt vmcnt(13)
	ds_write_b128 v143, v[102:105] offset:14848
	s_waitcnt vmcnt(12)
	ds_write_b128 v143, v[110:113] offset:16128
	ds_read2_b32 v[50:51], v142 offset0:96 offset1:100
	ds_read2_b32 v[66:67], v142 offset0:104 offset1:108
	ds_read2_b32 v[90:91], v142 offset0:112 offset1:116
	ds_read2_b32 v[110:111], v142 offset0:120 offset1:124
	ds_read_b128 v[114:117], v119 offset:7168
	ds_read_b128 v[120:123], v119 offset:7232
	ds_read_b128 v[174:177], v119 offset:7296
	ds_read_b128 v[178:181], v119 offset:7360
	s_waitcnt lgkmcnt(5)
	v_add_u32_e32 v42, s48, v50
	v_add_u32_e32 v50, s48, v51
	s_waitcnt lgkmcnt(4)
	v_add_u32_e32 v54, s48, v66
	v_add_u32_e32 v66, s48, v67
	s_waitcnt lgkmcnt(3)
	v_add_u32_e32 v78, s48, v90
	v_add_u32_e32 v90, s48, v91
	s_waitcnt lgkmcnt(2)
	v_add_u32_e32 v102, s48, v110
	v_add_u32_e32 v110, s48, v111
	v_ashrrev_i32_e32 v43, 31, v42
	v_ashrrev_i32_e32 v51, 31, v50
	v_ashrrev_i32_e32 v55, 31, v54
	v_ashrrev_i32_e32 v67, 31, v66
	v_ashrrev_i32_e32 v79, 31, v78
	v_ashrrev_i32_e32 v91, 31, v90
	v_ashrrev_i32_e32 v103, 31, v102
	v_ashrrev_i32_e32 v111, 31, v110
	v_lshlrev_b64 v[42:43], 9, v[42:43]
	v_lshlrev_b64 v[50:51], 9, v[50:51]
	v_lshlrev_b64 v[54:55], 9, v[54:55]
	v_lshlrev_b64 v[66:67], 9, v[66:67]
	v_lshlrev_b64 v[78:79], 9, v[78:79]
	v_lshlrev_b64 v[90:91], 9, v[90:91]
	v_lshlrev_b64 v[102:103], 9, v[102:103]
	v_lshlrev_b64 v[110:111], 9, v[110:111]
	v_lshl_add_u64 v[42:43], v[136:137], 0, v[42:43]
	v_lshl_add_u64 v[50:51], v[136:137], 0, v[50:51]
	v_lshl_add_u64 v[54:55], v[136:137], 0, v[54:55]
	v_lshl_add_u64 v[66:67], v[136:137], 0, v[66:67]
	v_lshl_add_u64 v[78:79], v[136:137], 0, v[78:79]
	v_lshl_add_u64 v[90:91], v[136:137], 0, v[90:91]
	v_lshl_add_u64 v[102:103], v[136:137], 0, v[102:103]
	v_lshl_add_u64 v[110:111], v[136:137], 0, v[110:111]
	global_load_dwordx4 v[42:45], v[42:43], off
	v_cndmask_b32_e64 v9, v9, 0, s[10:11]
	global_load_dwordx4 v[50:53], v[50:51], off
	v_cndmask_b32_e64 v8, v8, 0, s[10:11]
	global_load_dwordx4 v[54:57], v[54:55], off
	v_cndmask_b32_e64 v7, v7, 0, s[10:11]
	global_load_dwordx4 v[66:69], v[66:67], off
	v_cndmask_b32_e64 v6, v6, 0, s[10:11]
	global_load_dwordx4 v[78:81], v[78:79], off
	s_waitcnt lgkmcnt(1)
	v_mfma_f32_16x16x32_bf16 v[114:117], v[2:5], v[114:117], 0
	global_load_dwordx4 v[90:93], v[90:91], off
	v_cndmask_b32_e64 v13, v13, 0, s[10:11]
	global_load_dwordx4 v[102:105], v[102:103], off
	v_cndmask_b32_e64 v12, v12, 0, s[10:11]
	global_load_dwordx4 v[110:113], v[110:111], off
	v_cndmask_b32_e64 v11, v11, 0, s[10:11]
	v_cndmask_b32_e64 v10, v10, 0, s[10:11]
	s_waitcnt lgkmcnt(0)
	v_mfma_f32_16x16x32_bf16 v[114:117], v[6:9], v[120:123], v[114:117]
	s_nop 0
	v_cndmask_b32_e64 v17, v17, 0, s[10:11]
	v_cndmask_b32_e64 v16, v16, 0, s[10:11]
	v_cndmask_b32_e64 v15, v15, 0, s[10:11]
	v_cndmask_b32_e64 v14, v14, 0, s[10:11]
	s_waitcnt lgkmcnt(0)
	v_mfma_f32_16x16x32_bf16 v[114:117], v[10:13], v[174:177], v[114:117]
	s_nop 0
	v_cmp_gt_u32_e64 s[12:13], 16, v146
	s_waitcnt lgkmcnt(0)
	v_mfma_f32_16x16x32_bf16 v[114:117], v[14:17], v[178:181], v[114:117]
	s_and_saveexec_b64 s[0:1], s[12:13]
	s_nop 6
	ds_write_b128 v139, v[114:117] offset:1024
	s_or_b64 exec, exec, s[0:1]
	v_mul_u32_u24_e32 v114, 0x140, v1
	v_add_u32_e32 v140, v118, v114
	ds_read_b128 v[114:117], v140 offset:12288
	ds_read_b128 v[118:121], v140 offset:12352
	ds_read_b128 v[174:177], v140 offset:12416
	ds_read_b128 v[178:181], v140 offset:12480
	s_waitcnt lgkmcnt(1)
	v_mfma_f32_16x16x32_bf16 v[114:117], v[2:5], v[114:117], 0
	s_waitcnt lgkmcnt(0)
	v_mfma_f32_16x16x32_bf16 v[114:117], v[6:9], v[118:121], v[114:117]
	s_nop 0
	s_waitcnt lgkmcnt(0)
	v_mfma_f32_16x16x32_bf16 v[114:117], v[10:13], v[174:177], v[114:117]
	s_nop 0
	s_waitcnt lgkmcnt(0)
	v_mfma_f32_16x16x32_bf16 v[114:117], v[14:17], v[178:181], v[114:117]
	s_and_saveexec_b64 s[0:1], s[12:13]
	s_nop 6
	ds_write_b128 v139, v[114:117] offset:1280
	s_or_b64 exec, exec, s[0:1]
	s_waitcnt vmcnt(15)
	ds_write_b128 v143, v[18:21] offset:7168
	s_waitcnt vmcnt(14)
	ds_write_b128 v143, v[22:25] offset:8448
	ds_write_b128 v143, v[34:37] offset:9728
	ds_write_b128 v143, v[38:41] offset:11008
	ds_write_b128 v143, v[62:65] offset:12288
	ds_write_b128 v143, v[70:73] offset:13568
	ds_write_b128 v143, v[86:89] offset:14848
	ds_write_b128 v143, v[94:97] offset:16128
	ds_read2_b32 v[18:19], v142 offset0:128 offset1:132
	ds_read2_b32 v[20:21], v142 offset0:136 offset1:140
	s_waitcnt lgkmcnt(1)
	v_add_u32_e32 v22, s48, v18
	v_ashrrev_i32_e32 v23, 31, v22
	v_add_u32_e32 v18, s48, v19
	v_lshlrev_b64 v[22:23], 9, v[22:23]
	v_ashrrev_i32_e32 v19, 31, v18
	v_lshl_add_u64 v[22:23], v[136:137], 0, v[22:23]
	v_lshlrev_b64 v[18:19], 9, v[18:19]
	v_lshl_add_u64 v[18:19], v[136:137], 0, v[18:19]
	global_load_dwordx4 v[70:73], v[22:23], off
	global_load_dwordx4 v[86:89], v[18:19], off
	ds_read2_b32 v[22:23], v142 offset0:144 offset1:148
	s_waitcnt lgkmcnt(1)
	v_add_u32_e32 v18, s48, v20
	v_add_u32_e32 v20, s48, v21
	v_ashrrev_i32_e32 v19, 31, v18
	v_ashrrev_i32_e32 v21, 31, v20
	v_lshlrev_b64 v[18:19], 9, v[18:19]
	v_lshlrev_b64 v[20:21], 9, v[20:21]
	v_lshl_add_u64 v[18:19], v[136:137], 0, v[18:19]
	v_lshl_add_u64 v[20:21], v[136:137], 0, v[20:21]
	global_load_dwordx4 v[94:97], v[18:19], off
	global_load_dwordx4 v[114:117], v[20:21], off
	s_waitcnt lgkmcnt(0)
	v_add_u32_e32 v18, s48, v22
	v_add_u32_e32 v20, s48, v23
	ds_read2_b32 v[34:35], v142 offset0:152 offset1:156
	v_ashrrev_i32_e32 v19, 31, v18
	v_ashrrev_i32_e32 v21, 31, v20
	v_lshlrev_b64 v[18:19], 9, v[18:19]
	v_lshlrev_b64 v[20:21], 9, v[20:21]
	v_lshl_add_u64 v[18:19], v[136:137], 0, v[18:19]
	v_lshl_add_u64 v[20:21], v[136:137], 0, v[20:21]
	global_load_dwordx4 v[118:121], v[18:19], off
	global_load_dwordx4 v[122:125], v[20:21], off
	ds_read_b128 v[18:21], v140 offset:7168
	s_waitcnt lgkmcnt(1)
	v_add_u32_e32 v22, s48, v34
	v_ashrrev_i32_e32 v23, 31, v22
	v_lshlrev_b64 v[22:23], 9, v[22:23]
	v_lshl_add_u64 v[38:39], v[136:137], 0, v[22:23]
	ds_read_b128 v[22:25], v140 offset:7232
	s_waitcnt lgkmcnt(1)
	v_mfma_f32_16x16x32_bf16 v[18:21], v[2:5], v[18:21], 0
	v_add_u32_e32 v40, s48, v35
	v_ashrrev_i32_e32 v41, 31, v40
	ds_read_b128 v[34:37], v140 offset:7296
	s_waitcnt lgkmcnt(1)
	v_mfma_f32_16x16x32_bf16 v[18:21], v[6:9], v[22:25], v[18:21]
	v_lshlrev_b64 v[22:23], 9, v[40:41]
	v_lshl_add_u64 v[40:41], v[136:137], 0, v[22:23]
	ds_read_b128 v[22:25], v140 offset:7360
	global_load_dwordx4 v[126:129], v[38:39], off
	global_load_dwordx4 v[130:133], v[40:41], off
	s_waitcnt lgkmcnt(1)
	v_mfma_f32_16x16x32_bf16 v[18:21], v[10:13], v[34:37], v[18:21]
	s_waitcnt lgkmcnt(0)
	v_mfma_f32_16x16x32_bf16 v[18:21], v[14:17], v[22:25], v[18:21]
	s_and_saveexec_b64 s[0:1], s[12:13]
	s_nop 6
	ds_write_b128 v139, v[18:21] offset:1536
	s_or_b64 exec, exec, s[0:1]
	ds_read_b128 v[18:21], v140 offset:12288
	ds_read_b128 v[22:25], v140 offset:12352
	ds_read_b128 v[174:177], v140 offset:12416
	ds_read_b128 v[178:181], v140 offset:12480
	s_waitcnt lgkmcnt(1)
	v_mfma_f32_16x16x32_bf16 v[18:21], v[2:5], v[18:21], 0
	s_waitcnt lgkmcnt(0)
	v_mfma_f32_16x16x32_bf16 v[18:21], v[6:9], v[22:25], v[18:21]
	s_nop 0
	s_waitcnt lgkmcnt(0)
	v_mfma_f32_16x16x32_bf16 v[18:21], v[10:13], v[174:177], v[18:21]
	s_nop 0
	s_waitcnt lgkmcnt(0)
	v_mfma_f32_16x16x32_bf16 v[18:21], v[14:17], v[178:181], v[18:21]
	s_and_saveexec_b64 s[0:1], s[12:13]
	s_nop 6
	ds_write_b128 v139, v[18:21] offset:1792
	s_or_b64 exec, exec, s[0:1]
	s_waitcnt vmcnt(21)
	ds_write_b128 v143, v[26:29] offset:7168
	s_waitcnt vmcnt(20)
	ds_write_b128 v143, v[30:33] offset:8448
	ds_write_b128 v143, v[46:49] offset:9728
	ds_write_b128 v143, v[58:61] offset:11008
	s_waitcnt vmcnt(19)
	ds_write_b128 v143, v[74:77] offset:12288
	s_waitcnt vmcnt(18)
	ds_write_b128 v143, v[82:85] offset:13568
	s_waitcnt vmcnt(17)
	ds_write_b128 v143, v[98:101] offset:14848
	s_waitcnt vmcnt(16)
	ds_write_b128 v143, v[106:109] offset:16128
	ds_read2_b32 v[18:19], v142 offset0:160 offset1:164
	ds_read2_b32 v[26:27], v142 offset0:168 offset1:172
	s_waitcnt lgkmcnt(1)
	v_add_u32_e32 v20, s48, v18
	v_add_u32_e32 v18, s48, v19
	v_ashrrev_i32_e32 v21, 31, v20
	v_ashrrev_i32_e32 v19, 31, v18
	v_lshlrev_b64 v[20:21], 9, v[20:21]
	v_lshlrev_b64 v[18:19], 9, v[18:19]
	v_lshl_add_u64 v[20:21], v[136:137], 0, v[20:21]
	v_lshl_add_u64 v[22:23], v[136:137], 0, v[18:19]
	global_load_dwordx4 v[18:21], v[20:21], off
	s_nop 0
	global_load_dwordx4 v[22:25], v[22:23], off
	ds_read2_b32 v[34:35], v142 offset0:176 offset1:180
	s_waitcnt lgkmcnt(1)
	v_add_u32_e32 v28, s48, v26
	v_add_u32_e32 v26, s48, v27
	v_ashrrev_i32_e32 v29, 31, v28
	v_ashrrev_i32_e32 v27, 31, v26
	v_lshlrev_b64 v[28:29], 9, v[28:29]
	v_lshlrev_b64 v[26:27], 9, v[26:27]
	v_lshl_add_u64 v[28:29], v[136:137], 0, v[28:29]
	v_lshl_add_u64 v[30:31], v[136:137], 0, v[26:27]
	global_load_dwordx4 v[26:29], v[28:29], off
	s_nop 0
	global_load_dwordx4 v[30:33], v[30:31], off
	s_waitcnt lgkmcnt(0)
	v_add_u32_e32 v36, s48, v34
	v_add_u32_e32 v34, s48, v35
	ds_read2_b32 v[62:63], v142 offset0:184 offset1:188
	v_ashrrev_i32_e32 v37, 31, v36
	v_ashrrev_i32_e32 v35, 31, v34
	v_lshlrev_b64 v[36:37], 9, v[36:37]
	v_lshlrev_b64 v[34:35], 9, v[34:35]
	v_lshl_add_u64 v[36:37], v[136:137], 0, v[36:37]
	v_lshl_add_u64 v[38:39], v[136:137], 0, v[34:35]
	global_load_dwordx4 v[34:37], v[36:37], off
	s_nop 0
	global_load_dwordx4 v[38:41], v[38:39], off
	ds_read_b128 v[46:49], v140 offset:7168
	s_waitcnt lgkmcnt(1)
	v_add_u32_e32 v58, s48, v62
	v_ashrrev_i32_e32 v59, 31, v58
	v_lshlrev_b64 v[58:59], 9, v[58:59]
	v_lshl_add_u64 v[82:83], v[136:137], 0, v[58:59]
	ds_read_b128 v[58:61], v140 offset:7232
	s_waitcnt lgkmcnt(1)
	v_mfma_f32_16x16x32_bf16 v[46:49], v[2:5], v[46:49], 0
	v_add_u32_e32 v74, s48, v63
	ds_read_b128 v[62:65], v140 offset:7296
	v_ashrrev_i32_e32 v75, 31, v74
	s_waitcnt lgkmcnt(1)
	v_mfma_f32_16x16x32_bf16 v[46:49], v[6:9], v[58:61], v[46:49]
	v_lshlrev_b64 v[58:59], 9, v[74:75]
	v_lshl_add_u64 v[58:59], v[136:137], 0, v[58:59]
	ds_read_b128 v[74:77], v140 offset:7360
	s_waitcnt lgkmcnt(1)
	v_mfma_f32_16x16x32_bf16 v[62:65], v[10:13], v[62:65], v[46:49]
	s_nop 2
	global_load_dwordx4 v[46:49], v[82:83], off
	s_nop 0
	global_load_dwordx4 v[58:61], v[58:59], off
	s_waitcnt lgkmcnt(0)
	v_mfma_f32_16x16x32_bf16 v[62:65], v[14:17], v[74:77], v[62:65]
	s_and_saveexec_b64 s[0:1], s[12:13]
	s_nop 6
	ds_write_b128 v139, v[62:65] offset:2048
	s_or_b64 exec, exec, s[0:1]
	ds_read_b128 v[62:65], v140 offset:12288
	ds_read_b128 v[74:77], v140 offset:12352
	ds_read_b128 v[174:177], v140 offset:12416
	ds_read_b128 v[178:181], v140 offset:12480
	s_waitcnt lgkmcnt(1)
	v_mfma_f32_16x16x32_bf16 v[62:65], v[2:5], v[62:65], 0
	s_waitcnt lgkmcnt(0)
	v_mfma_f32_16x16x32_bf16 v[62:65], v[6:9], v[74:77], v[62:65]
	s_nop 0
	s_waitcnt lgkmcnt(0)
	v_mfma_f32_16x16x32_bf16 v[62:65], v[10:13], v[174:177], v[62:65]
	s_nop 0
	s_waitcnt lgkmcnt(0)
	v_mfma_f32_16x16x32_bf16 v[62:65], v[14:17], v[178:181], v[62:65]
	s_and_saveexec_b64 s[0:1], s[12:13]
	s_nop 6
	ds_write_b128 v139, v[62:65] offset:2304
	s_or_b64 exec, exec, s[0:1]
	s_waitcnt vmcnt(23)
	ds_write_b128 v143, v[42:45] offset:7168
	s_waitcnt vmcnt(22)
	ds_write_b128 v143, v[50:53] offset:8448
	s_waitcnt vmcnt(21)
	ds_write_b128 v143, v[54:57] offset:9728
	s_waitcnt vmcnt(20)
	ds_write_b128 v143, v[66:69] offset:11008
	s_waitcnt vmcnt(19)
	ds_write_b128 v143, v[78:81] offset:12288
	s_waitcnt vmcnt(18)
	ds_write_b128 v143, v[90:93] offset:13568
	s_waitcnt vmcnt(17)
	ds_write_b128 v143, v[102:105] offset:14848
	s_waitcnt vmcnt(16)
	ds_write_b128 v143, v[110:113] offset:16128
	ds_read2_b32 v[42:43], v142 offset0:192 offset1:196
	ds_read2_b32 v[54:55], v142 offset0:200 offset1:204
	s_waitcnt lgkmcnt(1)
	v_add_u32_e32 v44, s48, v42
	v_add_u32_e32 v42, s48, v43
	v_ashrrev_i32_e32 v45, 31, v44
	v_ashrrev_i32_e32 v43, 31, v42
	v_lshlrev_b64 v[44:45], 9, v[44:45]
	v_lshlrev_b64 v[42:43], 9, v[42:43]
	v_lshl_add_u64 v[44:45], v[136:137], 0, v[44:45]
	v_lshl_add_u64 v[50:51], v[136:137], 0, v[42:43]
	global_load_dwordx4 v[42:45], v[44:45], off
	s_nop 0
	global_load_dwordx4 v[50:53], v[50:51], off
	ds_read2_b32 v[66:67], v142 offset0:208 offset1:212
	s_waitcnt lgkmcnt(1)
	v_add_u32_e32 v56, s48, v54
	v_add_u32_e32 v54, s48, v55
	v_ashrrev_i32_e32 v57, 31, v56
	v_ashrrev_i32_e32 v55, 31, v54
	v_lshlrev_b64 v[56:57], 9, v[56:57]
	v_lshlrev_b64 v[54:55], 9, v[54:55]
	v_lshl_add_u64 v[56:57], v[136:137], 0, v[56:57]
	v_lshl_add_u64 v[62:63], v[136:137], 0, v[54:55]
	global_load_dwordx4 v[54:57], v[56:57], off
	s_nop 0
	global_load_dwordx4 v[62:65], v[62:63], off
	s_waitcnt lgkmcnt(0)
	v_add_u32_e32 v68, s48, v66
	v_add_u32_e32 v66, s48, v67
	ds_read2_b32 v[90:91], v142 offset0:216 offset1:220
	v_ashrrev_i32_e32 v69, 31, v68
	v_ashrrev_i32_e32 v67, 31, v66
	v_lshlrev_b64 v[68:69], 9, v[68:69]
	v_lshlrev_b64 v[66:67], 9, v[66:67]
	v_lshl_add_u64 v[68:69], v[136:137], 0, v[68:69]
	v_lshl_add_u64 v[74:75], v[136:137], 0, v[66:67]
	global_load_dwordx4 v[66:69], v[68:69], off
	s_nop 0
	global_load_dwordx4 v[74:77], v[74:75], off
	ds_read_b128 v[78:81], v140 offset:7168
	s_waitcnt lgkmcnt(1)
	v_add_u32_e32 v82, s48, v90
	v_ashrrev_i32_e32 v83, 31, v82
	v_lshlrev_b64 v[82:83], 9, v[82:83]
	v_lshl_add_u64 v[102:103], v[136:137], 0, v[82:83]
	ds_read_b128 v[82:85], v140 offset:7232
	s_waitcnt lgkmcnt(1)
	v_mfma_f32_16x16x32_bf16 v[78:81], v[2:5], v[78:81], 0
	v_add_u32_e32 v98, s48, v91
	ds_read_b128 v[90:93], v140 offset:7296
	v_ashrrev_i32_e32 v99, 31, v98
	s_waitcnt lgkmcnt(1)
	v_mfma_f32_16x16x32_bf16 v[78:81], v[6:9], v[82:85], v[78:81]
	v_lshlrev_b64 v[82:83], 9, v[98:99]
	v_lshl_add_u64 v[82:83], v[136:137], 0, v[82:83]
	ds_read_b128 v[98:101], v140 offset:7360
	s_waitcnt lgkmcnt(1)
	v_mfma_f32_16x16x32_bf16 v[90:93], v[10:13], v[90:93], v[78:81]
	s_nop 2
	global_load_dwordx4 v[78:81], v[102:103], off
	s_nop 0
	global_load_dwordx4 v[82:85], v[82:83], off
	s_waitcnt lgkmcnt(0)
	v_mfma_f32_16x16x32_bf16 v[90:93], v[14:17], v[98:101], v[90:93]
	s_and_saveexec_b64 s[0:1], s[12:13]
	s_nop 6
	ds_write_b128 v139, v[90:93] offset:2560
	s_or_b64 exec, exec, s[0:1]
	ds_read_b128 v[90:93], v140 offset:12288
	ds_read_b128 v[98:101], v140 offset:12352
	ds_read_b128 v[174:177], v140 offset:12416
	ds_read_b128 v[178:181], v140 offset:12480
	s_waitcnt lgkmcnt(1)
	v_mfma_f32_16x16x32_bf16 v[90:93], v[2:5], v[90:93], 0
	s_waitcnt lgkmcnt(0)
	v_mfma_f32_16x16x32_bf16 v[90:93], v[6:9], v[98:101], v[90:93]
	s_nop 0
	s_waitcnt lgkmcnt(0)
	v_mfma_f32_16x16x32_bf16 v[90:93], v[10:13], v[174:177], v[90:93]
	s_nop 0
	s_waitcnt lgkmcnt(0)
	v_mfma_f32_16x16x32_bf16 v[90:93], v[14:17], v[178:181], v[90:93]
	s_and_saveexec_b64 s[0:1], s[12:13]
	s_nop 6
	ds_write_b128 v139, v[90:93] offset:2816
	s_or_b64 exec, exec, s[0:1]
	s_waitcnt vmcnt(23)
	ds_write_b128 v143, v[70:73] offset:7168
	s_waitcnt vmcnt(22)
	ds_write_b128 v143, v[86:89] offset:8448
	s_waitcnt vmcnt(21)
	ds_write_b128 v143, v[94:97] offset:9728
	s_waitcnt vmcnt(20)
	ds_write_b128 v143, v[114:117] offset:11008
	s_waitcnt vmcnt(19)
	ds_write_b128 v143, v[118:121] offset:12288
	s_waitcnt vmcnt(18)
	ds_write_b128 v143, v[122:125] offset:13568
	s_waitcnt vmcnt(17)
	ds_write_b128 v143, v[126:129] offset:14848
	s_waitcnt vmcnt(16)
	ds_write_b128 v143, v[130:133] offset:16128
	ds_read2_b32 v[86:87], v142 offset0:224 offset1:228
	ds_read2_b32 v[94:95], v142 offset0:232 offset1:236
	ds_read2_b32 v[102:103], v142 offset0:240 offset1:244
	ds_read2_b32 v[110:111], v142 offset0:248 offset1:252
	ds_read_b128 v[114:117], v140 offset:7168
	ds_read_b128 v[118:121], v140 offset:7232
	ds_read_b128 v[174:177], v140 offset:7296
	ds_read_b128 v[178:181], v140 offset:7360
	s_waitcnt lgkmcnt(5)
	v_add_u32_e32 v70, s48, v86
	v_add_u32_e32 v86, s48, v87
	s_waitcnt lgkmcnt(4)
	v_add_u32_e32 v90, s48, v94
	v_add_u32_e32 v94, s48, v95
	s_waitcnt lgkmcnt(3)
	v_add_u32_e32 v98, s48, v102
	v_add_u32_e32 v102, s48, v103
	s_waitcnt lgkmcnt(2)
	v_add_u32_e32 v106, s48, v110
	v_add_u32_e32 v110, s48, v111
	v_ashrrev_i32_e32 v71, 31, v70
	v_ashrrev_i32_e32 v87, 31, v86
	v_ashrrev_i32_e32 v91, 31, v90
	v_ashrrev_i32_e32 v95, 31, v94
	v_ashrrev_i32_e32 v99, 31, v98
	v_ashrrev_i32_e32 v103, 31, v102
	v_ashrrev_i32_e32 v107, 31, v106
	v_ashrrev_i32_e32 v111, 31, v110
	v_lshlrev_b64 v[70:71], 9, v[70:71]
	v_lshlrev_b64 v[86:87], 9, v[86:87]
	v_lshlrev_b64 v[90:91], 9, v[90:91]
	v_lshlrev_b64 v[94:95], 9, v[94:95]
	v_lshlrev_b64 v[98:99], 9, v[98:99]
	v_lshlrev_b64 v[102:103], 9, v[102:103]
	v_lshlrev_b64 v[106:107], 9, v[106:107]
	v_lshlrev_b64 v[110:111], 9, v[110:111]
	v_lshl_add_u64 v[70:71], v[136:137], 0, v[70:71]
	v_lshl_add_u64 v[86:87], v[136:137], 0, v[86:87]
	v_lshl_add_u64 v[90:91], v[136:137], 0, v[90:91]
	v_lshl_add_u64 v[94:95], v[136:137], 0, v[94:95]
	v_lshl_add_u64 v[98:99], v[136:137], 0, v[98:99]
	v_lshl_add_u64 v[102:103], v[136:137], 0, v[102:103]
	v_lshl_add_u64 v[106:107], v[136:137], 0, v[106:107]
	v_lshl_add_u64 v[110:111], v[136:137], 0, v[110:111]
	global_load_dwordx4 v[70:73], v[70:71], off
	s_waitcnt lgkmcnt(1)
	v_mfma_f32_16x16x32_bf16 v[114:117], v[2:5], v[114:117], 0
	global_load_dwordx4 v[86:89], v[86:87], off
	s_nop 0
	global_load_dwordx4 v[90:93], v[90:91], off
	s_waitcnt lgkmcnt(0)
	v_mfma_f32_16x16x32_bf16 v[114:117], v[6:9], v[118:121], v[114:117]
	global_load_dwordx4 v[94:97], v[94:95], off
	s_nop 0
	global_load_dwordx4 v[98:101], v[98:99], off
	s_waitcnt lgkmcnt(0)
	v_mfma_f32_16x16x32_bf16 v[114:117], v[10:13], v[174:177], v[114:117]
	global_load_dwordx4 v[102:105], v[102:103], off
	s_nop 0
	global_load_dwordx4 v[106:109], v[106:107], off
	s_waitcnt lgkmcnt(0)
	v_mfma_f32_16x16x32_bf16 v[114:117], v[14:17], v[178:181], v[114:117]
	global_load_dwordx4 v[110:113], v[110:111], off
	s_and_saveexec_b64 s[0:1], s[12:13]
	s_nop 5
	ds_write_b128 v139, v[114:117] offset:3072
	s_or_b64 exec, exec, s[0:1]
	ds_read_b128 v[114:117], v140 offset:12288
	ds_read_b128 v[118:121], v140 offset:12352
	ds_read_b128 v[174:177], v140 offset:12416
	ds_read_b128 v[178:181], v140 offset:12480
	s_waitcnt lgkmcnt(1)
	v_mfma_f32_16x16x32_bf16 v[114:117], v[2:5], v[114:117], 0
	s_waitcnt lgkmcnt(0)
	v_mfma_f32_16x16x32_bf16 v[114:117], v[6:9], v[118:121], v[114:117]
	s_nop 0
	s_waitcnt lgkmcnt(0)
	v_mfma_f32_16x16x32_bf16 v[114:117], v[10:13], v[174:177], v[114:117]
	s_nop 0
	s_waitcnt lgkmcnt(0)
	v_mfma_f32_16x16x32_bf16 v[114:117], v[14:17], v[178:181], v[114:117]
	s_and_saveexec_b64 s[0:1], s[12:13]
	s_nop 6
	ds_write_b128 v139, v[114:117] offset:3328
	s_or_b64 exec, exec, s[0:1]
	s_waitcnt vmcnt(23)
	ds_write_b128 v143, v[18:21] offset:7168
	s_waitcnt vmcnt(22)
	ds_write_b128 v143, v[22:25] offset:8448
	s_waitcnt vmcnt(21)
	ds_write_b128 v143, v[26:29] offset:9728
	s_waitcnt vmcnt(20)
	ds_write_b128 v143, v[30:33] offset:11008
	s_waitcnt vmcnt(19)
	ds_write_b128 v143, v[34:37] offset:12288
	s_waitcnt vmcnt(18)
	ds_write_b128 v143, v[38:41] offset:13568
	s_waitcnt vmcnt(17)
	ds_write_b128 v143, v[46:49] offset:14848
	s_waitcnt vmcnt(16)
	ds_write_b128 v143, v[58:61] offset:16128
	ds_read_b128 v[18:21], v140 offset:7168
	ds_read_b128 v[22:25], v140 offset:7232
	s_waitcnt lgkmcnt(1)
	v_mfma_f32_16x16x32_bf16 v[18:21], v[2:5], v[18:21], 0
	s_waitcnt lgkmcnt(0)
	v_mfma_f32_16x16x32_bf16 v[18:21], v[6:9], v[22:25], v[18:21]
	ds_read_b128 v[22:25], v140 offset:7296
	ds_read_b128 v[26:29], v140 offset:7360
	s_waitcnt lgkmcnt(1)
	v_mfma_f32_16x16x32_bf16 v[18:21], v[10:13], v[22:25], v[18:21]
	s_waitcnt lgkmcnt(0)
	v_mfma_f32_16x16x32_bf16 v[18:21], v[14:17], v[26:29], v[18:21]
	s_and_saveexec_b64 s[0:1], s[12:13]
	s_nop 6
	ds_write_b128 v139, v[18:21] offset:3584
	s_or_b64 exec, exec, s[0:1]
	ds_read_b128 v[18:21], v140 offset:12288
	ds_read_b128 v[22:25], v140 offset:12352
	ds_read_b128 v[174:177], v140 offset:12416
	ds_read_b128 v[178:181], v140 offset:12480
	s_waitcnt lgkmcnt(1)
	v_mfma_f32_16x16x32_bf16 v[18:21], v[2:5], v[18:21], 0
	s_waitcnt lgkmcnt(0)
	v_mfma_f32_16x16x32_bf16 v[18:21], v[6:9], v[22:25], v[18:21]
	s_nop 0
	s_waitcnt lgkmcnt(0)
	v_mfma_f32_16x16x32_bf16 v[18:21], v[10:13], v[174:177], v[18:21]
	s_nop 0
	s_waitcnt lgkmcnt(0)
	v_mfma_f32_16x16x32_bf16 v[18:21], v[14:17], v[178:181], v[18:21]
	s_and_saveexec_b64 s[0:1], s[12:13]
	s_nop 6
	ds_write_b128 v139, v[18:21] offset:3840
	s_or_b64 exec, exec, s[0:1]
	s_waitcnt vmcnt(15)
	ds_write_b128 v143, v[42:45] offset:7168
	s_waitcnt vmcnt(14)
	ds_write_b128 v143, v[50:53] offset:8448
	s_waitcnt vmcnt(13)
	ds_write_b128 v143, v[54:57] offset:9728
	s_waitcnt vmcnt(12)
	ds_write_b128 v143, v[62:65] offset:11008
	s_waitcnt vmcnt(11)
	ds_write_b128 v143, v[66:69] offset:12288
	s_waitcnt vmcnt(10)
	ds_write_b128 v143, v[74:77] offset:13568
	s_waitcnt vmcnt(9)
	ds_write_b128 v143, v[78:81] offset:14848
	s_waitcnt vmcnt(8)
	ds_write_b128 v143, v[82:85] offset:16128
	ds_read_b128 v[18:21], v140 offset:7168
	ds_read_b128 v[22:25], v140 offset:7232
	s_waitcnt lgkmcnt(1)
	v_mfma_f32_16x16x32_bf16 v[18:21], v[2:5], v[18:21], 0
	s_waitcnt lgkmcnt(0)
	v_mfma_f32_16x16x32_bf16 v[18:21], v[6:9], v[22:25], v[18:21]
	ds_read_b128 v[22:25], v140 offset:7296
	ds_read_b128 v[26:29], v140 offset:7360
	s_waitcnt lgkmcnt(1)
	v_mfma_f32_16x16x32_bf16 v[18:21], v[10:13], v[22:25], v[18:21]
	s_waitcnt lgkmcnt(0)
	v_mfma_f32_16x16x32_bf16 v[18:21], v[14:17], v[26:29], v[18:21]
	s_and_saveexec_b64 s[0:1], s[12:13]
	s_nop 6
	ds_write_b128 v139, v[18:21] offset:4096
	s_or_b64 exec, exec, s[0:1]
	ds_read_b128 v[18:21], v140 offset:12288
	ds_read_b128 v[22:25], v140 offset:12352
	ds_read_b128 v[174:177], v140 offset:12416
	ds_read_b128 v[178:181], v140 offset:12480
	s_waitcnt lgkmcnt(1)
	v_mfma_f32_16x16x32_bf16 v[18:21], v[2:5], v[18:21], 0
	s_waitcnt lgkmcnt(0)
	v_mfma_f32_16x16x32_bf16 v[18:21], v[6:9], v[22:25], v[18:21]
	s_nop 0
	s_waitcnt lgkmcnt(0)
	v_mfma_f32_16x16x32_bf16 v[18:21], v[10:13], v[174:177], v[18:21]
	s_nop 0
	s_waitcnt lgkmcnt(0)
	v_mfma_f32_16x16x32_bf16 v[18:21], v[14:17], v[178:181], v[18:21]
	s_and_saveexec_b64 s[0:1], s[12:13]
	s_nop 6
	ds_write_b128 v139, v[18:21] offset:4352
	s_or_b64 exec, exec, s[0:1]
	s_waitcnt vmcnt(7)
	ds_write_b128 v143, v[70:73] offset:7168
	s_waitcnt vmcnt(6)
	ds_write_b128 v143, v[86:89] offset:8448
	s_waitcnt vmcnt(5)
	ds_write_b128 v143, v[90:93] offset:9728
	s_waitcnt vmcnt(4)
	ds_write_b128 v143, v[94:97] offset:11008
	s_waitcnt vmcnt(3)
	ds_write_b128 v143, v[98:101] offset:12288
	s_waitcnt vmcnt(2)
	ds_write_b128 v143, v[102:105] offset:13568
	s_waitcnt vmcnt(1)
	ds_write_b128 v143, v[106:109] offset:14848
	s_waitcnt vmcnt(0)
	ds_write_b128 v143, v[110:113] offset:16128
	ds_read_b128 v[18:21], v140 offset:7168
	ds_read_b128 v[22:25], v140 offset:7232
	s_waitcnt lgkmcnt(1)
	v_mfma_f32_16x16x32_bf16 v[18:21], v[2:5], v[18:21], 0
	s_waitcnt lgkmcnt(0)
	v_mfma_f32_16x16x32_bf16 v[18:21], v[6:9], v[22:25], v[18:21]
	ds_read_b128 v[22:25], v140 offset:7296
	ds_read_b128 v[26:29], v140 offset:7360
	s_waitcnt lgkmcnt(1)
	v_mfma_f32_16x16x32_bf16 v[18:21], v[10:13], v[22:25], v[18:21]
	s_waitcnt lgkmcnt(0)
	v_mfma_f32_16x16x32_bf16 v[18:21], v[14:17], v[26:29], v[18:21]
	s_and_saveexec_b64 s[0:1], s[12:13]
	s_nop 6
	ds_write_b128 v139, v[18:21] offset:4608
	s_or_b64 exec, exec, s[0:1]
	ds_read_b128 v[18:21], v140 offset:12288
	s_waitcnt lgkmcnt(0)
	v_mfma_f32_16x16x32_bf16 v[2:5], v[2:5], v[18:21], 0
	ds_read_b128 v[18:21], v140 offset:12352
	s_waitcnt lgkmcnt(0)
	v_mfma_f32_16x16x32_bf16 v[2:5], v[6:9], v[18:21], v[2:5]
	ds_read_b128 v[6:9], v140 offset:12416
	s_waitcnt lgkmcnt(0)
	v_mfma_f32_16x16x32_bf16 v[2:5], v[10:13], v[6:9], v[2:5]
	ds_read_b128 v[6:9], v140 offset:12480
	s_waitcnt lgkmcnt(0)
	v_mfma_f32_16x16x32_bf16 v[2:5], v[14:17], v[6:9], v[2:5]
	s_and_saveexec_b64 s[0:1], s[12:13]
	s_nop 6
	ds_write_b128 v139, v[2:5] offset:4864
	s_or_b64 exec, exec, s[0:1]
	ds_read2_b32 v[2:3], v142 offset1:4
	s_lshl_b32 s0, s4, 7
	s_lshl_b32 s0, s0, 1
	v_lshlrev_b32_e32 v4, 3, v1
	s_add_u32 s0, s60, s0
	s_addc_u32 s1, s61, 0
	v_lshlrev_b32_e32 v4, 1, v4
	v_mov_b32_e32 v5, v135
	v_lshl_add_u64 v[130:131], s[0:1], 0, v[4:5]
	ds_read2_b32 v[4:5], v142 offset0:8 offset1:12
	s_waitcnt lgkmcnt(1)
	v_add_u32_e32 v6, s48, v2
	v_ashrrev_i32_e32 v7, 31, v6
	v_add_u32_e32 v2, s48, v3
	v_lshlrev_b64 v[6:7], 9, v[6:7]
	v_ashrrev_i32_e32 v3, 31, v2
	v_lshl_add_u64 v[6:7], v[130:131], 0, v[6:7]
	v_lshlrev_b64 v[2:3], 9, v[2:3]
	v_lshl_add_u64 v[2:3], v[130:131], 0, v[2:3]
	global_load_dwordx4 v[10:13], v[6:7], off
	global_load_dwordx4 v[18:21], v[2:3], off
	ds_read2_b32 v[6:7], v142 offset0:16 offset1:20
	s_waitcnt lgkmcnt(1)
	v_add_u32_e32 v2, s48, v4
	v_add_u32_e32 v4, s48, v5
	v_ashrrev_i32_e32 v3, 31, v2
	v_ashrrev_i32_e32 v5, 31, v4
	v_lshlrev_b64 v[2:3], 9, v[2:3]
	v_lshlrev_b64 v[4:5], 9, v[4:5]
	v_lshl_add_u64 v[2:3], v[130:131], 0, v[2:3]
	v_lshl_add_u64 v[4:5], v[130:131], 0, v[4:5]
	global_load_dwordx4 v[30:33], v[2:3], off
	global_load_dwordx4 v[38:41], v[4:5], off
	s_waitcnt lgkmcnt(0)
	v_add_u32_e32 v2, s48, v6
	v_add_u32_e32 v4, s48, v7
	ds_read2_b32 v[6:7], v142 offset0:24 offset1:28
	v_ashrrev_i32_e32 v3, 31, v2
	v_lshlrev_b64 v[2:3], 9, v[2:3]
	v_ashrrev_i32_e32 v5, 31, v4
	v_lshl_add_u64 v[2:3], v[130:131], 0, v[2:3]
	v_lshlrev_b64 v[4:5], 9, v[4:5]
	v_lshl_add_u64 v[4:5], v[130:131], 0, v[4:5]
	global_load_dwordx4 v[50:53], v[2:3], off
	global_load_dwordx4 v[54:57], v[4:5], off
	s_waitcnt lgkmcnt(0)
	v_add_u32_e32 v2, s48, v6
	v_ashrrev_i32_e32 v3, 31, v2
	v_add_u32_e32 v4, s48, v7
	v_lshlrev_b64 v[2:3], 9, v[2:3]
	v_ashrrev_i32_e32 v5, 31, v4
	v_lshl_add_u64 v[2:3], v[130:131], 0, v[2:3]
	v_lshlrev_b64 v[4:5], 9, v[4:5]
	v_lshl_add_u64 v[4:5], v[130:131], 0, v[4:5]
	global_load_dwordx4 v[58:61], v[2:3], off
	global_load_dwordx4 v[62:65], v[4:5], off
	v_cndmask_b32_e64 v2, 0, 1, s[6:7]
	v_cmp_ne_u32_e64 s[16:17], 1, v2
	s_andn2_b64 vcc, exec, s[6:7]
	s_cbranch_vccnz .LBB0_2593
	ds_read2_b32 v[2:3], v142 offset0:32 offset1:36
	ds_read2_b32 v[14:15], v142 offset0:40 offset1:44
	s_waitcnt lgkmcnt(1)
	v_add_u32_e32 v2, s48, v2
	v_add_u32_e32 v4, s48, v3
	s_waitcnt lgkmcnt(0)
	v_add_u32_e32 v16, s48, v14
	v_add_u32_e32 v14, s48, v15
	v_ashrrev_i32_e32 v3, 31, v2
	v_ashrrev_i32_e32 v5, 31, v4
	v_ashrrev_i32_e32 v17, 31, v16
	v_ashrrev_i32_e32 v15, 31, v14
	v_lshlrev_b64 v[2:3], 9, v[2:3]
	v_lshlrev_b64 v[4:5], 9, v[4:5]
	v_lshlrev_b64 v[16:17], 9, v[16:17]
	v_lshlrev_b64 v[14:15], 9, v[14:15]
	v_lshl_add_u64 v[2:3], v[130:131], 0, v[2:3]
	v_lshl_add_u64 v[6:7], v[130:131], 0, v[4:5]
	v_lshl_add_u64 v[16:17], v[130:131], 0, v[16:17]
	v_lshl_add_u64 v[22:23], v[130:131], 0, v[14:15]
	global_load_dwordx4 v[2:5], v[2:3], off
	s_nop 0
	global_load_dwordx4 v[6:9], v[6:7], off
	ds_read2_b32 v[26:27], v142 offset0:48 offset1:52
	global_load_dwordx4 v[14:17], v[16:17], off
	s_nop 0
	global_load_dwordx4 v[22:25], v[22:23], off
	ds_read2_b32 v[42:43], v142 offset0:56 offset1:60
	s_waitcnt lgkmcnt(1)
	v_add_u32_e32 v28, s48, v26
	v_add_u32_e32 v26, s48, v27
	s_waitcnt lgkmcnt(0)
	v_add_u32_e32 v44, s48, v42
	v_add_u32_e32 v42, s48, v43
	v_ashrrev_i32_e32 v29, 31, v28
	v_ashrrev_i32_e32 v27, 31, v26
	v_ashrrev_i32_e32 v45, 31, v44
	v_ashrrev_i32_e32 v43, 31, v42
	v_lshlrev_b64 v[28:29], 9, v[28:29]
	v_lshlrev_b64 v[26:27], 9, v[26:27]
	v_lshlrev_b64 v[44:45], 9, v[44:45]
	v_lshlrev_b64 v[42:43], 9, v[42:43]
	v_lshl_add_u64 v[28:29], v[130:131], 0, v[28:29]
	v_lshl_add_u64 v[34:35], v[130:131], 0, v[26:27]
	v_lshl_add_u64 v[44:45], v[130:131], 0, v[44:45]
	v_lshl_add_u64 v[46:47], v[130:131], 0, v[42:43]
	global_load_dwordx4 v[26:29], v[28:29], off
	s_nop 0
	global_load_dwordx4 v[34:37], v[34:35], off
	s_nop 0
	global_load_dwordx4 v[42:45], v[44:45], off
	s_nop 0
	global_load_dwordx4 v[46:49], v[46:47], off
